# P3 chunk tail: K' scaling moved into the section that writes h, so the LDS barrier between it and the gate/state-update region is gone (6 barriers per chunk instead of 7)
# speedup vs baseline: 1.0073x; 1.0007x over previous
.LBB0_773:
	s_or_b64 exec, exec, s[0:1]
	s_add_i32 s0, 0, 0x21000
	s_waitcnt lgkmcnt(0)
	s_barrier
	v_lshl_add_u32 v121, v143, 2, s0
	ds_read_b128 v[234:237], v121
	s_waitcnt lgkmcnt(1)
	v_lshlrev_b32_e32 v134, 6, v196
	v_cmp_gt_i32_e64 s[6:7], s86, v132
	v_or_b32_e32 v188, 1, v182
	s_and_b64 s[8:9], s[2:3], s[6:7]
	s_waitcnt lgkmcnt(0)
	v_mul_f32_e32 v48, v48, v234
	v_bfe_u32 v121, v48, 16, 1
	v_mul_f32_e32 v49, v49, v235
	v_add3_u32 v48, v48, v121, s68
	ds_write_b16_d16_hi v222, v48
	v_bfe_u32 v48, v49, 16, 1
	v_add3_u32 v48, v49, v48, s68
	ds_write_b16_d16_hi v225, v48
	v_mul_f32_e32 v48, v50, v236
	v_bfe_u32 v49, v48, 16, 1
	v_add3_u32 v48, v48, v49, s68
	ds_write_b16_d16_hi v229, v48
	v_lshl_add_u32 v48, v113, 2, s0
	ds_read_b128 v[238:241], v48
	v_mul_f32_e32 v48, v51, v237
	v_bfe_u32 v49, v48, 16, 1
	v_add3_u32 v48, v48, v49, s68
	ds_write_b16_d16_hi v211, v48
	s_waitcnt lgkmcnt(1)
	v_mul_f32_e32 v48, v52, v238
	v_bfe_u32 v49, v48, 16, 1
	v_add3_u32 v48, v48, v49, s68
	ds_write_b16_d16_hi v207, v48
	v_mul_f32_e32 v48, v53, v239
	v_bfe_u32 v49, v48, 16, 1
	v_add3_u32 v48, v48, v49, s68
	ds_write_b16_d16_hi v210, v48
	v_mul_f32_e32 v48, v54, v240
	v_bfe_u32 v49, v48, 16, 1
	v_add3_u32 v48, v48, v49, s68
	ds_write_b16_d16_hi v214, v48
	v_lshl_add_u32 v48, v126, 2, s0
	ds_read_b128 v[48:51], v48
	v_mul_f32_e32 v52, v55, v241
	v_bfe_u32 v53, v52, 16, 1
	v_add3_u32 v52, v52, v53, s68
	ds_write_b16_d16_hi v213, v52
	s_waitcnt lgkmcnt(1)
	v_mul_f32_e32 v52, v56, v48
	v_bfe_u32 v53, v52, 16, 1
	v_add3_u32 v52, v52, v53, s68
	ds_write_b16_d16_hi v215, v52
	v_mul_f32_e32 v52, v57, v49
	v_bfe_u32 v53, v52, 16, 1
	v_add3_u32 v52, v52, v53, s68
	ds_write_b16_d16_hi v217, v52
	v_mul_f32_e32 v52, v58, v50
	v_bfe_u32 v53, v52, 16, 1
	v_add3_u32 v52, v52, v53, s68
	ds_write_b16_d16_hi v219, v52
	v_lshl_add_u32 v52, v123, 2, s0
	ds_read_b128 v[52:55], v52
	v_mul_f32_e32 v56, v59, v51
	v_bfe_u32 v57, v56, 16, 1
	v_add3_u32 v56, v56, v57, s68
	ds_write_b16_d16_hi v204, v56
	s_waitcnt lgkmcnt(1)
	v_mul_f32_e32 v56, v60, v52
	v_bfe_u32 v57, v56, 16, 1
	v_add3_u32 v56, v56, v57, s68
	ds_write_b16_d16_hi v202, v56
	v_mul_f32_e32 v56, v61, v53
	v_bfe_u32 v57, v56, 16, 1
	v_add3_u32 v56, v56, v57, s68
	ds_write_b16_d16_hi v203, v56
	v_mul_f32_e32 v56, v62, v54
	v_bfe_u32 v57, v56, 16, 1
	v_add3_u32 v56, v56, v57, s68
	ds_write_b16_d16_hi v205, v56
	v_mul_f32_e32 v56, v63, v55
	v_bfe_u32 v57, v56, 16, 1
	v_add3_u32 v56, v56, v57, s68
	v_mul_f32_e32 v32, v32, v234
	ds_write_b16_d16_hi v206, v56
	v_bfe_u32 v56, v32, 16, 1
	v_add3_u32 v32, v32, v56, s68
	ds_write_b16_d16_hi v208, v32
	v_mul_f32_e32 v32, v33, v235
	v_bfe_u32 v33, v32, 16, 1
	v_add3_u32 v32, v32, v33, s68
	ds_write_b16_d16_hi v209, v32
	v_mul_f32_e32 v32, v34, v236
	v_bfe_u32 v33, v32, 16, 1
	v_add3_u32 v32, v32, v33, s68
	ds_write_b16_d16_hi v212, v32
	v_mul_f32_e32 v32, v35, v237
	v_bfe_u32 v33, v32, 16, 1
	v_add3_u32 v32, v32, v33, s68
	ds_write_b16_d16_hi v216, v32
	v_mul_f32_e32 v32, v36, v238
	v_bfe_u32 v33, v32, 16, 1
	v_add3_u32 v32, v32, v33, s68
	ds_write_b16_d16_hi v218, v32
	v_mul_f32_e32 v32, v37, v239
	v_bfe_u32 v33, v32, 16, 1
	v_add3_u32 v32, v32, v33, s68
	ds_write_b16_d16_hi v220, v32
	v_mul_f32_e32 v32, v38, v240
	v_bfe_u32 v33, v32, 16, 1
	v_add3_u32 v32, v32, v33, s68
	ds_write_b16_d16_hi v221, v32
	v_mul_f32_e32 v32, v39, v241
	v_bfe_u32 v33, v32, 16, 1
	v_add3_u32 v32, v32, v33, s68
	ds_write_b16_d16_hi v223, v32
	v_mul_f32_e32 v32, v40, v48
	v_bfe_u32 v33, v32, 16, 1
	v_add3_u32 v32, v32, v33, s68
	ds_write_b16_d16_hi v224, v32
	v_mul_f32_e32 v32, v41, v49
	v_bfe_u32 v33, v32, 16, 1
	v_add3_u32 v32, v32, v33, s68
	ds_write_b16_d16_hi v226, v32
	v_mul_f32_e32 v32, v42, v50
	v_bfe_u32 v33, v32, 16, 1
	v_add3_u32 v32, v32, v33, s68
	ds_write_b16_d16_hi v227, v32
	v_mul_f32_e32 v32, v43, v51
	v_bfe_u32 v33, v32, 16, 1
	v_add3_u32 v32, v32, v33, s68
	ds_write_b16_d16_hi v228, v32
	v_mul_f32_e32 v32, v44, v52
	v_bfe_u32 v33, v32, 16, 1
	v_add3_u32 v32, v32, v33, s68
	ds_write_b16_d16_hi v230, v32
	v_mul_f32_e32 v32, v45, v53
	v_bfe_u32 v33, v32, 16, 1
	v_add3_u32 v32, v32, v33, s68
	ds_write_b16_d16_hi v231, v32
	v_mul_f32_e32 v32, v46, v54
	v_bfe_u32 v33, v32, 16, 1
	v_add3_u32 v32, v32, v33, s68
	ds_write_b16_d16_hi v232, v32
	v_mul_f32_e32 v32, v47, v55
	v_bfe_u32 v33, v32, 16, 1
	v_add3_u32 v32, v32, v33, s68
	v_ashrrev_i32_e32 v121, 31, v120
	ds_write_b16_d16_hi v233, v32
	v_lshl_add_u64 v[32:33], s[66:67], 0, v[120:121]
	v_lshlrev_b64 v[34:35], 13, v[32:33]
	v_lshl_add_u64 v[38:39], s[52:53], 0, v[34:35]
	ds_read_b128 v[42:45], v191 offset:32768
	v_add_u32_e32 v32, 0x20c00, v192
	ds_read_b32 v40, v32
	s_waitcnt lgkmcnt(1)
	v_and_b32_e32 v35, 0xffff0000, v43
	v_and_b32_e32 v34, 0xffff0000, v42
	v_and_b32_e32 v39, 0xffff0000, v45
	v_and_b32_e32 v38, 0xffff0000, v44
	v_lshlrev_b32_e32 v33, 16, v43
	v_lshlrev_b32_e32 v32, 16, v42
	s_waitcnt lgkmcnt(0)
	v_pk_mul_f32 v[34:35], v[40:41], v[34:35] op_sel_hi:[0,1]
	v_lshlrev_b32_e32 v37, 16, v45
	v_lshlrev_b32_e32 v36, 16, v44
	v_pk_mul_f32 v[38:39], v[40:41], v[38:39] op_sel_hi:[0,1]
	v_pk_mul_f32 v[32:33], v[40:41], v[32:33] op_sel_hi:[0,1]
	v_pk_mul_f32 v[36:37], v[40:41], v[36:37] op_sel_hi:[0,1]
	v_bfe_u32 v41, v39, 16, 1
	v_bfe_u32 v42, v38, 16, 1
	v_bfe_u32 v43, v35, 16, 1
	v_bfe_u32 v44, v34, 16, 1
	v_add3_u32 v44, v34, v44, s68
	v_add3_u32 v43, v35, v43, s68
	v_add3_u32 v34, v38, v42, s68
	v_add3_u32 v35, v39, v41, s68
	v_bfe_u32 v41, v36, 16, 1
	v_bfe_u32 v42, v37, 16, 1
	v_add3_u32 v37, v37, v42, s68
	v_add3_u32 v36, v36, v41, s68
	v_bfe_u32 v38, v32, 16, 1
	v_bfe_u32 v39, v33, 16, 1
	v_lshrrev_b32_e32 v41, 16, v36
	v_lshrrev_b32_e32 v36, 16, v37
	v_add3_u32 v33, v33, v39, s68
	v_add3_u32 v32, v32, v38, s68
	v_and_or_b32 v35, v35, s82, v36
	ds_read_b128 v[36:39], v190 offset:32768
	v_lshrrev_b32_e32 v32, 16, v32
	v_lshrrev_b32_e32 v33, 16, v33
	v_and_or_b32 v34, v34, s82, v41
	v_and_or_b32 v33, v43, s82, v33
	v_and_or_b32 v32, v44, s82, v32
	ds_write_b128 v191, v[32:35] offset:32768
	s_waitcnt lgkmcnt(1)
	v_lshlrev_b32_e32 v33, 16, v37
	v_lshlrev_b32_e32 v32, 16, v36
	v_and_b32_e32 v35, 0xffff0000, v37
	v_and_b32_e32 v34, 0xffff0000, v36
	v_lshlrev_b32_e32 v37, 16, v39
	v_lshlrev_b32_e32 v36, 16, v38
	v_and_b32_e32 v39, 0xffff0000, v39
	v_and_b32_e32 v38, 0xffff0000, v38
	v_pk_mul_f32 v[34:35], v[40:41], v[34:35] op_sel_hi:[0,1]
	v_pk_mul_f32 v[38:39], v[40:41], v[38:39] op_sel_hi:[0,1]
	v_pk_mul_f32 v[32:33], v[40:41], v[32:33] op_sel_hi:[0,1]
	v_pk_mul_f32 v[36:37], v[40:41], v[36:37] op_sel_hi:[0,1]
	v_bfe_u32 v41, v39, 16, 1
	v_bfe_u32 v42, v38, 16, 1
	v_bfe_u32 v43, v35, 16, 1
	v_bfe_u32 v44, v34, 16, 1
	v_add3_u32 v44, v34, v44, s68
	v_add3_u32 v43, v35, v43, s68
	v_add3_u32 v34, v38, v42, s68
	v_add3_u32 v35, v39, v41, s68
	v_bfe_u32 v41, v36, 16, 1
	v_bfe_u32 v42, v37, 16, 1
	v_add3_u32 v37, v37, v42, s68
	v_add3_u32 v36, v36, v41, s68
	v_bfe_u32 v38, v32, 16, 1
	v_bfe_u32 v39, v33, 16, 1
	v_lshrrev_b32_e32 v41, 16, v36
	v_lshrrev_b32_e32 v36, 16, v37
	v_add3_u32 v33, v33, v39, s68
	v_add3_u32 v32, v32, v38, s68
	v_and_or_b32 v35, v35, s82, v36
	ds_read_b128 v[36:39], v161 offset:32768
	v_lshrrev_b32_e32 v32, 16, v32
	v_lshrrev_b32_e32 v33, 16, v33
	v_and_or_b32 v34, v34, s82, v41
	v_and_or_b32 v33, v43, s82, v33
	v_and_or_b32 v32, v44, s82, v32
	ds_write_b128 v190, v[32:35] offset:32768
	s_waitcnt lgkmcnt(1)
	v_lshlrev_b32_e32 v33, 16, v37
	v_lshlrev_b32_e32 v32, 16, v36
	v_and_b32_e32 v35, 0xffff0000, v37
	v_and_b32_e32 v34, 0xffff0000, v36
	v_pk_mul_f32 v[36:37], v[40:41], v[32:33] op_sel_hi:[0,1]
	v_pk_mul_f32 v[32:33], v[40:41], v[34:35] op_sel_hi:[0,1]
	v_lshlrev_b32_e32 v35, 16, v39
	v_lshlrev_b32_e32 v34, 16, v38
	v_and_b32_e32 v39, 0xffff0000, v39
	v_and_b32_e32 v38, 0xffff0000, v38
	v_pk_mul_f32 v[42:43], v[40:41], v[34:35] op_sel_hi:[0,1]
	v_pk_mul_f32 v[34:35], v[40:41], v[38:39] op_sel_hi:[0,1]
	v_bfe_u32 v38, v35, 16, 1
	v_bfe_u32 v44, v32, 16, 1
	v_bfe_u32 v39, v34, 16, 1
	v_bfe_u32 v41, v33, 16, 1
	v_add3_u32 v32, v32, v44, s68
	v_add3_u32 v35, v35, v38, s68
	v_bfe_u32 v38, v36, 16, 1
	v_bfe_u32 v44, v43, 16, 1
	v_add3_u32 v33, v33, v41, s68
	v_add3_u32 v34, v34, v39, s68
	v_bfe_u32 v39, v37, 16, 1
	v_bfe_u32 v41, v42, 16, 1
	v_add3_u32 v44, v43, v44, s68
	v_add3_u32 v36, v36, v38, s68
	v_add3_u32 v43, v42, v41, s68
	v_add3_u32 v37, v37, v39, s68
	v_lshrrev_b32_e32 v41, 16, v36
	v_lshrrev_b32_e32 v36, 16, v44
	v_lshrrev_b32_e32 v42, 16, v37
	v_and_or_b32 v35, v35, s82, v36
	ds_read_b128 v[36:39], v117 offset:32768
	v_lshrrev_b32_e32 v43, 16, v43
	v_and_or_b32 v34, v34, s82, v43
	v_and_or_b32 v33, v33, s82, v42
	v_and_or_b32 v32, v32, s82, v41
	ds_write_b128 v161, v[32:35] offset:32768
	s_waitcnt lgkmcnt(1)
	v_lshlrev_b32_e32 v33, 16, v37
	v_lshlrev_b32_e32 v32, 16, v36
	v_and_b32_e32 v35, 0xffff0000, v37
	v_and_b32_e32 v34, 0xffff0000, v36
	v_lshlrev_b32_e32 v37, 16, v39
	v_lshlrev_b32_e32 v36, 16, v38
	v_and_b32_e32 v39, 0xffff0000, v39
	v_and_b32_e32 v38, 0xffff0000, v38
	v_pk_mul_f32 v[34:35], v[40:41], v[34:35] op_sel_hi:[0,1]
	v_pk_mul_f32 v[38:39], v[40:41], v[38:39] op_sel_hi:[0,1]
	v_pk_mul_f32 v[32:33], v[40:41], v[32:33] op_sel_hi:[0,1]
	v_pk_mul_f32 v[36:37], v[40:41], v[36:37] op_sel_hi:[0,1]
	v_bfe_u32 v40, v39, 16, 1
	v_bfe_u32 v41, v38, 16, 1
	v_bfe_u32 v42, v35, 16, 1
	v_bfe_u32 v43, v34, 16, 1
	v_add3_u32 v43, v34, v43, s68
	v_add3_u32 v42, v35, v42, s68
	v_add3_u32 v34, v38, v41, s68
	v_add3_u32 v35, v39, v40, s68
	v_bfe_u32 v38, v32, 16, 1
	v_bfe_u32 v39, v33, 16, 1
	v_bfe_u32 v40, v36, 16, 1
	v_bfe_u32 v41, v37, 16, 1
	v_add3_u32 v37, v37, v41, s68
	v_add3_u32 v36, v36, v40, s68
	v_add3_u32 v33, v33, v39, s68
	v_add3_u32 v32, v32, v38, s68
	v_lshrrev_b32_e32 v32, 16, v32
	v_lshrrev_b32_e32 v33, 16, v33
	v_lshrrev_b32_e32 v36, 16, v36
	v_lshrrev_b32_e32 v37, 16, v37
	v_and_or_b32 v35, v35, s82, v37
	v_and_or_b32 v34, v34, s82, v36
	v_and_or_b32 v33, v42, s82, v33
	v_and_or_b32 v32, v43, s82, v32
	ds_write_b128 v117, v[32:35] offset:32768
	s_and_saveexec_b64 s[0:1], s[8:9]
	s_cbranch_execz .LBB0_775
	v_lshl_add_u32 v32, v132, 2, 0
	v_add_u32_e32 v32, 0x20e00, v32
	ds_read_b32 v33, v32
	s_waitcnt lgkmcnt(0)
	v_mul_f32_e32 v33, v109, v33
	ds_write_b32 v32, v33
